# one static s_setprio 1 for the second-dispatched block of every CU for the whole kernel
# baseline (speedup 1.0000x reference)
; #define LAS __attribute__((address_space(3)))
; __global__ void __launch_bounds__(256, 2) k_mega(P p) {
;   __shared__ __attribute__((aligned(16))) char smem[SMEM_BYTES];
;   cg::grid_group grid = cg::this_grid();
;   __shared__ __attribute__((aligned(16))) unsigned xb_words[4];
;   if (threadIdx.x < 4) xb_words[threadIdx.x] = 0u;
;   __syncthreads();
;   const XcdBarrier xb = xcd_barrier_post((unsigned*)(p.ws + OFF_BAR), (volatile LAS unsigned*)xb_words);
; #pragma unroll 1
;   for (int step = 0; step < 20; ++step) {
;     int ph, l = 0, hf = 0;
;     if (step < 2) ph = step;
;     else {
;       const int s = step - 2;
;       l = s / 9;
;       const int k = s - l * 9;
;       ph = (k == 0) ? PH_PROJ : (k == 1 ? 14 : k + 5);
;     }
;     P q = p;
;     size_t z0 = 0;
;     asm volatile("" : "+s"(z0));
;     q.ws = p.ws + z0;
;     q.out = p.out + z0;
;     if (ph == 14) phase_mixer(q, l, xb, smem);
;     else run_phase(q, ph, l, hf, smem);
.LBB0_5:
	s_or_b64 exec, exec, s[12:13]
	s_load_dwordx16 s[76:91], s[0:1], 0x0
	s_load_dwordx16 s[12:27], s[0:1], 0x40
	s_load_dwordx16 s[40:55], s[0:1], 0x80
	s_load_dwordx16 s[56:71], s[0:1], 0xc0
	s_mul_i32 s0, s73, s72
	s_waitcnt lgkmcnt(0)
	s_add_u32 s2, s88, 0x1000
	s_addc_u32 s3, s89, 0
	v_writelane_b32 v252, s2, 9
	v_lshrrev_b32_e32 v1, 20, v0
	v_lshrrev_b32_e32 v0, 10, v0
	v_writelane_b32 v252, s3, 10
	s_add_u32 s2, s16, 0x1920000
	s_addc_u32 s3, s17, 0
	v_writelane_b32 v252, s2, 11
	v_or_b32_e32 v0, v0, v1
	s_movk_i32 s74, 0xff80
	v_writelane_b32 v252, s3, 12
	s_add_u32 s2, s22, 0x120000
	s_addc_u32 s3, s23, 0
	v_writelane_b32 v252, s2, 13
	v_mov_b32_e32 v1, 0
	v_mov_b32_e32 v224, 0x358637bd
	v_writelane_b32 v252, s3, 14
	s_add_u32 s2, s24, 0x100000
	v_writelane_b32 v252, s12, 15
	s_addc_u32 s3, s25, 0
	s_movk_i32 s28, 0x90
	v_writelane_b32 v252, s13, 16
	v_writelane_b32 v252, s14, 17
	v_writelane_b32 v252, s15, 18
	v_writelane_b32 v252, s16, 19
	v_writelane_b32 v252, s17, 20
	v_writelane_b32 v252, s18, 21
	v_writelane_b32 v252, s19, 22
	v_writelane_b32 v252, s20, 23
	v_writelane_b32 v252, s21, 24
	v_writelane_b32 v252, s22, 25
	v_writelane_b32 v252, s23, 26
	v_writelane_b32 v252, s24, 27
	v_writelane_b32 v252, s25, 28
	v_writelane_b32 v252, s26, 29
	v_writelane_b32 v252, s27, 30
	v_writelane_b32 v252, s2, 31
	s_movk_i32 s29, 0xc0
	s_mov_b32 s75, -1
	v_writelane_b32 v252, s3, 32
	s_add_u32 s2, s52, 0x40000
	v_writelane_b32 v252, s40, 33
	s_addc_u32 s3, s53, 0
	s_mov_b32 s30, 0x3e16c740
	v_writelane_b32 v252, s41, 34
	v_writelane_b32 v252, s42, 35
	v_writelane_b32 v252, s43, 36
	v_writelane_b32 v252, s44, 37
	v_writelane_b32 v252, s45, 38
	v_writelane_b32 v252, s46, 39
	v_writelane_b32 v252, s47, 40
	v_writelane_b32 v252, s48, 41
	v_writelane_b32 v252, s49, 42
	v_writelane_b32 v252, s50, 43
	v_writelane_b32 v252, s51, 44
	v_writelane_b32 v252, s52, 45
	v_writelane_b32 v252, s53, 46
	v_writelane_b32 v252, s54, 47
	v_writelane_b32 v252, s55, 48
	v_writelane_b32 v252, s2, 49
	v_mov_b32_e32 v225, 0x7f800000
	s_nop 0
	v_writelane_b32 v252, s3, 50
	s_add_u32 s2, s64, 0x600000
	s_addc_u32 s3, s65, 0
	v_writelane_b32 v252, s2, 51
	s_nop 1
	v_writelane_b32 v252, s3, 52
	s_add_u32 s2, s64, 0x800000
	s_addc_u32 s3, s65, 0
	v_writelane_b32 v252, s2, 53
	s_nop 1
	v_writelane_b32 v252, s3, 54
	s_add_u32 s2, s64, 0xa00000
	s_addc_u32 s3, s65, 0
	v_writelane_b32 v252, s2, 55
	s_nop 1
	v_writelane_b32 v252, s3, 56
	s_add_u32 s2, s66, 0x400000
	s_addc_u32 s3, s67, 0
	v_writelane_b32 v252, s2, 57
	s_nop 1
	v_writelane_b32 v252, s3, 58
	s_add_u32 s2, s68, 0x1600000
	s_addc_u32 s3, s69, 0
	v_writelane_b32 v252, s2, 59
	s_nop 1
	v_writelane_b32 v252, s3, 60
	s_add_u32 s2, s70, 0xb00000
	s_addc_u32 s3, s71, 0
	v_writelane_b32 v252, s2, 61
	s_lshr_b32 s1, s72, 3
	s_nop 0
	v_writelane_b32 v252, s3, 62
	v_writelane_b32 v252, s1, 63
	s_ashr_i32 s1, s72, 3
	s_lshl_b32 s2, s72, 2
	v_writelane_b32 v253, s1, 0
	s_lshl_b32 s1, s72, 8
	s_add_u32 s6, s64, 0x200000
	v_writelane_b32 v253, s1, 1
	s_addc_u32 s7, s65, 0
	v_writelane_b32 v253, s6, 2
	v_readlane_b32 s12, v252, 0
	v_readlane_b32 s14, v252, 2
	v_writelane_b32 v253, s7, 3
	s_add_u32 s6, s64, 0x400000
	v_writelane_b32 v253, s56, 4
	s_addc_u32 s7, s65, 0
	s_add_i32 s3, s72, 0xffffff80
	v_writelane_b32 v253, s57, 5
	v_writelane_b32 v253, s58, 6
	v_writelane_b32 v253, s59, 7
	v_writelane_b32 v253, s60, 8
	v_writelane_b32 v253, s61, 9
	v_writelane_b32 v253, s62, 10
	v_writelane_b32 v253, s63, 11
	v_writelane_b32 v253, s64, 12
	v_writelane_b32 v253, s65, 13
	v_writelane_b32 v253, s66, 14
	s_lshl_b32 s20, s3, 2
	v_writelane_b32 v253, s67, 15
	v_readlane_b32 s15, v252, 3
	s_add_u32 s92, s14, 0x1e2ec300
	v_writelane_b32 v253, s68, 16
	s_addc_u32 s93, s15, 0
	v_writelane_b32 v253, s69, 17
	s_add_u32 s94, s14, 0x1e2ec500
	v_writelane_b32 v253, s70, 18
	s_addc_u32 s95, s15, 0
	v_writelane_b32 v253, s71, 19
	s_add_u32 s22, s14, 0x1e2ec600
	v_writelane_b32 v253, s6, 20
	s_addc_u32 s23, s15, 0
	v_readlane_b32 s13, v252, 1
	v_writelane_b32 v253, s7, 21
	s_add_u32 s6, s14, 0x1e2ec700
	s_addc_u32 s7, s15, 0
	v_writelane_b32 v253, s6, 22
	s_mov_b64 s[66:67], 0x1000
	s_mov_b32 s64, 0x800000
	v_writelane_b32 v253, s7, 23
	s_add_u32 s6, s14, 0x1e2ec800
	s_addc_u32 s7, s15, 0
	v_writelane_b32 v253, s6, 24
	s_movk_i32 s65, 0x1000
	s_mov_b32 s68, 0
	v_writelane_b32 v253, s7, 25
	s_add_u32 s6, s14, 0x1e2ec900
	s_addc_u32 s7, s15, 0
	v_writelane_b32 v253, s6, 26
	s_nop 1
	v_writelane_b32 v253, s7, 27
	s_add_u32 s6, s14, 0x1e2eca00
	s_addc_u32 s7, s15, 0
	v_writelane_b32 v253, s6, 28
	s_nop 1
	v_writelane_b32 v253, s7, 29
	s_add_u32 s6, s14, 0x1e2ecb00
	s_addc_u32 s7, s15, 0
	v_writelane_b32 v253, s6, 30
	s_nop 1
	v_writelane_b32 v253, s7, 31
	s_add_u32 s6, s14, 0x1e2ecc00
	s_addc_u32 s7, s15, 0
	v_writelane_b32 v253, s6, 32
	s_nop 1
	v_writelane_b32 v253, s7, 33
	s_add_u32 s6, s14, 0x1e2ecd00
	s_addc_u32 s7, s15, 0
	v_writelane_b32 v253, s6, 34
	s_nop 1
	v_writelane_b32 v253, s7, 35
	s_add_u32 s6, s14, 0x1e2ece00
	s_addc_u32 s7, s15, 0
	v_writelane_b32 v253, s6, 36
	s_nop 1
	v_writelane_b32 v253, s7, 37
	s_add_u32 s6, s14, 0x1e2ecf00
	s_addc_u32 s7, s15, 0
	v_writelane_b32 v253, s6, 38
	s_nop 1
	v_writelane_b32 v253, s7, 39
	s_add_u32 s6, s14, 0x1e2ed000
	s_addc_u32 s7, s15, 0
	v_writelane_b32 v253, s6, 40
	s_nop 1
	v_writelane_b32 v253, s7, 41
; DI unsigned xb_ld(unsigned* p) { return __hip_atomic_load(p, __ATOMIC_RELAXED, __HIP_MEMORY_SCOPE_AGENT); }
; DI void xcd_barrier_complete(unsigned* bar, unsigned x, unsigned& nloc, unsigned& nx) {
;   const unsigned G = gridDim.x * gridDim.y * gridDim.z;
;   unsigned sum, cnt, mine, sp = 0u;
;   for (;;) {
;     sum = 0u; cnt = 0u; mine = 0u;
; #pragma unroll
;     for (unsigned j = 0; j < 16; ++j) { const unsigned c = xb_ld(&bar[XB_XCNT(j)]); sum += c; cnt += (c > 0u) ? 1u : 0u; mine = (j == x) ? c : mine; }
;     if (sum == G) break;
;     __builtin_amdgcn_s_sleep(1);
;     if ((++sp & 255u) == 0u) { if (xb_ld(&bar[XB_TMO])) break; if (sp > XB_SPIN_CAP) { atomicAdd(&bar[XB_TMO], 1u); break; } }
;   }
;   nloc = mine > 0u ? mine : 1u; nx = cnt > 0u ? cnt : 1u;
; }
; __global__ void __launch_bounds__(256, 2) k_mega(P p) {
;     ...
;     if (step < 19) xcd_barrier(xb);
;     if (gridDim.y == 7777u) grid.sync();
	s_add_u32 s6, s14, 0x1e2ed100
	s_addc_u32 s7, s15, 0
	v_writelane_b32 v253, s6, 42
	s_nop 1
	v_writelane_b32 v253, s7, 43
	s_add_u32 s6, s14, 0x1e2ed200
	s_addc_u32 s7, s15, 0
	v_writelane_b32 v253, s6, 44
	s_nop 1
	v_writelane_b32 v253, s7, 45
	s_add_u32 s6, s14, 0x1e2ed300
	s_addc_u32 s7, s15, 0
	v_writelane_b32 v253, s6, 46
	s_nop 1
	v_writelane_b32 v253, s7, 47
	s_add_u32 s6, s14, 0x1e2ed400
	s_addc_u32 s7, s15, 0
	v_writelane_b32 v253, s6, 48
	s_cmp_eq_u32 s8, 15
	s_nop 0
	v_writelane_b32 v253, s7, 49
	s_cselect_b64 s[6:7], -1, 0
	v_writelane_b32 v253, s6, 50
	s_cmp_eq_u32 s8, 14
	s_nop 0
	v_writelane_b32 v253, s7, 51
	s_cselect_b64 s[6:7], -1, 0
	v_writelane_b32 v253, s6, 52
	s_cmp_eq_u32 s8, 13
	s_nop 0
	v_writelane_b32 v253, s7, 53
	s_cselect_b64 s[6:7], -1, 0
	v_writelane_b32 v253, s6, 54
	s_cmp_eq_u32 s8, 12
	s_nop 0
	v_writelane_b32 v253, s7, 55
	s_cselect_b64 s[6:7], -1, 0
	v_writelane_b32 v253, s6, 56
	s_cmp_eq_u32 s8, 11
	s_nop 0
	v_writelane_b32 v253, s7, 57
	s_cselect_b64 s[6:7], -1, 0
	v_writelane_b32 v253, s6, 58
	s_cmp_eq_u32 s8, 10
	s_nop 0
	v_writelane_b32 v253, s7, 59
	s_cselect_b64 s[6:7], -1, 0
	v_writelane_b32 v253, s6, 60
	s_cmp_eq_u32 s8, 9
	s_nop 0
	v_writelane_b32 v253, s7, 61
	s_cselect_b64 s[6:7], -1, 0
	v_writelane_b32 v253, s6, 62
	s_cmp_eq_u32 s8, 8
	s_nop 0
	v_writelane_b32 v253, s7, 63
	s_cselect_b64 s[6:7], -1, 0
	v_writelane_b32 v254, s6, 0
	s_cmp_eq_u32 s8, 7
	s_nop 0
	v_writelane_b32 v254, s7, 1
	s_cselect_b64 s[6:7], -1, 0
	v_writelane_b32 v254, s6, 2
	s_cmp_eq_u32 s8, 6
	s_nop 0
	v_writelane_b32 v254, s7, 3
	s_cselect_b64 s[6:7], -1, 0
	v_writelane_b32 v254, s6, 4
	s_cmp_eq_u32 s8, 5
	s_nop 0
	v_writelane_b32 v254, s7, 5
	s_cselect_b64 s[6:7], -1, 0
	v_writelane_b32 v254, s6, 6
	s_cmp_eq_u32 s8, 4
	s_nop 0
	v_writelane_b32 v254, s7, 7
	s_cselect_b64 s[6:7], -1, 0
	v_writelane_b32 v254, s6, 8
	s_cmp_eq_u32 s8, 3
	s_nop 0
	v_writelane_b32 v254, s7, 9
	s_cselect_b64 s[6:7], -1, 0
	v_writelane_b32 v254, s6, 10
	s_cmp_eq_u32 s8, 2
	s_nop 0
	v_writelane_b32 v254, s7, 11
	s_cselect_b64 s[6:7], -1, 0
	v_writelane_b32 v254, s6, 12
	s_cmp_eq_u32 s8, 1
	s_nop 0
	v_writelane_b32 v254, s7, 13
	s_cselect_b64 s[6:7], -1, 0
	v_writelane_b32 v254, s6, 14
	s_cmp_eq_u32 s8, 0
	s_nop 0
	v_writelane_b32 v254, s7, 15
	s_cselect_b64 s[6:7], -1, 0
	s_lshl_b32 s1, s9, 2
	s_add_u32 s1, s4, s1
	v_writelane_b32 v254, s6, 16
	s_addc_u32 s4, s5, 0
	s_nop 0
	v_writelane_b32 v254, s7, 17
	s_add_u32 s6, s1, 0x1400
	s_addc_u32 s7, s4, 0
	v_writelane_b32 v254, s6, 18
	s_nop 1
	v_writelane_b32 v254, s7, 19
	s_add_u32 s6, s1, 0x2400
	s_addc_u32 s7, s4, 0
	v_writelane_b32 v254, s6, 20
	s_add_u32 s4, s14, 0x1e2ef500
	s_addc_u32 s5, s15, 0
	v_writelane_b32 v254, s7, 21
	v_writelane_b32 v254, s4, 22
	s_nop 1
	v_writelane_b32 v254, s5, 23
	s_add_u32 s4, s14, 0x1e2ef600
	s_addc_u32 s5, s15, 0
	v_writelane_b32 v254, s4, 24
	s_ashr_i32 s1, s3, 3
	s_cmpk_eq_i32 s73, 0x1e61
	v_writelane_b32 v254, s5, 25
	v_writelane_b32 v254, s3, 26
	v_writelane_b32 v254, s1, 27
	v_readlane_b32 s1, v252, 4
	s_mul_i32 s0, s0, s1
	v_writelane_b32 v254, s0, 28
	s_cselect_b64 s[0:1], -1, 0
	v_writelane_b32 v254, s0, 29
	s_ashr_i32 s3, s2, 31
	s_nop 0
	v_writelane_b32 v254, s1, 30
	s_movk_i32 s0, 0x3ff
	v_and_or_b32 v0, v0, s0, v203
	v_cmp_eq_u32_e64 s[0:1], 0, v0
	s_nop 1
	v_writelane_b32 v254, s0, 31
	s_nop 1
	v_writelane_b32 v254, s1, 32
	s_lshl_b64 s[0:1], s[2:3], 12
	v_writelane_b32 v254, s0, 33
	s_nop 1
	v_writelane_b32 v254, s1, 34
	s_add_u32 s0, s14, 0x17cec080
	v_writelane_b32 v254, s0, 35
	s_addc_u32 s0, s15, 0
	v_writelane_b32 v254, s0, 36
	s_add_u32 s0, s14, 0x80
	v_writelane_b32 v254, s0, 37
	s_addc_u32 s0, s15, 0
	v_writelane_b32 v254, s0, 38
	s_lshl_b32 s0, s72, 5
	v_writelane_b32 v254, s0, 39
	s_lshl_b32 s0, s72, 7
	v_writelane_b32 v254, s0, 40
	s_add_u32 s0, s14, 0xf4ec280
	s_addc_u32 s1, s15, 0
	s_mov_b64 s[4:5], s[76:77]
	s_mov_b64 s[12:13], s[84:85]
	v_writelane_b32 v254, s0, 41
	s_add_u32 s12, s12, 0x5a000
	s_addc_u32 s13, s13, 0
	v_writelane_b32 v254, s1, 42
	v_writelane_b32 v254, s12, 43
	s_mul_i32 s0, s72, 0x1400
	s_mul_hi_i32 s1, s2, 0x500
	v_writelane_b32 v254, s13, 44
	v_writelane_b32 v254, s0, 45
	s_mov_b64 s[6:7], s[78:79]
	s_mov_b64 s[8:9], s[80:81]
	v_writelane_b32 v254, s1, 46
	s_add_i32 s0, s0, 0xfff60000
	v_writelane_b32 v254, s20, 47
	s_mul_hi_i32 s1, s20, 0x500
	v_writelane_b32 v254, s0, 48
	s_mov_b64 s[10:11], s[82:83]
	s_mov_b64 s[14:15], s[86:87]
	v_writelane_b32 v254, s1, 49
	v_writelane_b32 v254, s31, 50
	v_writelane_b32 v254, s72, 51
	s_mov_b64 s[16:17], s[88:89]
	s_mov_b64 s[18:19], s[90:91]
	v_writelane_b32 v254, s73, 52
	v_writelane_b32 v254, s4, 53
	s_mov_b64 s[90:91], s[22:23]
	s_mov_b32 s87, 0x8000
	v_writelane_b32 v254, s5, 54
	v_writelane_b32 v254, s6, 55
	v_writelane_b32 v254, s7, 56
	v_writelane_b32 v254, s8, 57
	v_writelane_b32 v255, s15, 0
	v_writelane_b32 v254, s9, 58
	v_writelane_b32 v255, s16, 1
	v_writelane_b32 v254, s10, 59
	v_writelane_b32 v255, s17, 2
	v_writelane_b32 v254, s11, 60
	v_writelane_b32 v255, s18, 3
	v_writelane_b32 v254, s12, 61
	v_writelane_b32 v255, s19, 4
	v_writelane_b32 v254, s13, 62
	v_writelane_b32 v255, s2, 5
	s_movk_i32 s76, 0x50
	s_mov_b32 s79, 0x41000000
	v_writelane_b32 v254, s14, 63
	v_writelane_b32 v255, s3, 6
	s_lshr_b32 s98, s31, 3
	s_cmp_ge_u32 s98, 32
	s_cbranch_scc0 .Lprio_glob_done
	s_setprio 1
